# speedup vs baseline: 1.0008x; 1.0008x over previous
; template <bool BOUNDARY, bool Q0, bool Q1>
; __device__ __forceinline__ void attn_tile(const bf16* Ks, const bf16* Vt, const bf16x8 (&Qf)[2][2], const uint32_t (&vm)[2],
;                                           float (&m)[2], float (&l)[2], f32x4 (&O)[4][2], int fr, int fq) {
;     ...
; #pragma unroll
;   for (int kt = 0; kt < 4; ++kt) {
;     S[kt][0] = f32x4{0.f, 0.f, 0.f, 0.f};
;     S[kt][1] = f32x4{0.f, 0.f, 0.f, 0.f};
; #pragma unroll
;     for (int ks = 0; ks < 2; ++ks) {
;       const bf16x8 kf = *(const bf16x8*)(Ks + (16 * kt + fr) * KS_LD + 32 * ks + 8 * fq);
;       if (Q0) S[kt][0] = __builtin_amdgcn_mfma_f32_16x16x32_bf16(kf, Qf[0][ks], S[kt][0], 0, 0, 0);
;       if (Q1) S[kt][1] = __builtin_amdgcn_mfma_f32_16x16x32_bf16(kf, Qf[1][ks], S[kt][1], 0, 0, 0);
;     }
;   }
; #pragma unroll
;   for (int qt = 0; qt < 2; ++qt) {
;     if ((qt == 0 && !Q0) || (qt == 1 && !Q1)) continue;
;     float mx, mxu;
;     if (BOUNDARY) {
;       mx = m[qt];
; #pragma unroll
;       for (int kt = 0; kt < 4; ++kt)
; #pragma unroll
;         for (int j = 0; j < 4; ++j) {
;           const float s2 = S[kt][qt][j];
;           if ((vm[qt] >> (kt * 4 + j)) & 1u) mx = fmaxf(mx, s2);
;         }
;       mx = fmaxf(mx, __shfl_xor(mx, 16));
;       mx = fmaxf(mx, __shfl_xor(mx, 32));
;       mxu = mx;
;     } else {
;       float rm = -3.0e38f;
; #pragma unroll
;       for (int kt = 0; kt < 4; ++kt)
; #pragma unroll
;         for (int j = 0; j < 4; ++j) {
;           rm = fmaxf(rm, S[kt][qt][j]);
;         }
;       rm = fmaxf(rm, __shfl_xor(rm, 16));
;       rm = fmaxf(rm, __shfl_xor(rm, 32));
;       const bool rv = vm[qt] != 0u;
;       mx = rv ? fmaxf(m[qt], rm) : m[qt];
;       mxu = rv ? mx : 3.0e38f;
;     }
;     const float alpha = __builtin_amdgcn_exp2f(m[qt] - mx);
;     m[qt] = mx;
;     float ls = 0.f;
; #pragma unroll
;     for (int kt = 0; kt < 4; ++kt)
; #pragma unroll
;       for (int j = 0; j < 4; ++j) {
;         float pv;
;         if (BOUNDARY) pv = ((vm[qt] >> (kt * 4 + j)) & 1u) ? __builtin_amdgcn_exp2f(S[kt][qt][j] - mxu) : 0.f;
;         else pv = __builtin_amdgcn_exp2f(S[kt][qt][j] - mxu);
;         S[kt][qt][j] = pv;
;         ls += pv;
;       }
;     l[qt] = l[qt] * alpha + ls;
.LBB0_665:
	s_andn2_b64 vcc, exec, s[8:9]
	s_cbranch_vccnz .LBB0_675
	v_add_u32_e32 v104, v138, v152
	v_add_u32_e32 v147, v104, v230
	v_add_u32_e32 v143, v104, v163
	ds_read_b128 v[100:103], v147
	ds_read_b128 v[144:147], v147 offset:64
	ds_read_b128 v[96:99], v143
	ds_read_b128 v[108:111], v143 offset:64
	ds_read_b128 v[92:95], v143 offset:2304
	ds_read_b128 v[104:107], v143 offset:4608
	v_cmp_ne_u32_e32 vcc, 0, v142
	s_waitcnt lgkmcnt(5)
	v_mfma_f32_16x16x32_bf16 v[120:123], v[100:103], v[0:3], 0
	v_mfma_f32_16x16x32_bf16 v[100:103], v[100:103], v[8:11], 0
	s_waitcnt lgkmcnt(4)
	v_mfma_f32_16x16x32_bf16 v[120:123], v[144:147], v[4:7], v[120:123]
	v_mfma_f32_16x16x32_bf16 v[100:103], v[144:147], v[12:15], v[100:103]
	ds_read_b128 v[144:147], v143 offset:2368
	s_waitcnt lgkmcnt(3)
	v_mfma_f32_16x16x32_bf16 v[116:119], v[96:99], v[0:3], 0
	v_mfma_f32_16x16x32_bf16 v[96:99], v[96:99], v[8:11], 0
	v_mfma_f32_16x16x32_bf16 v[116:119], v[108:111], v[4:7], v[116:119]
	v_mfma_f32_16x16x32_bf16 v[96:99], v[108:111], v[12:15], v[96:99]
	s_waitcnt lgkmcnt(0)
	v_mfma_f32_16x16x32_bf16 v[112:115], v[92:95], v[0:3], 0
	v_mfma_f32_16x16x32_bf16 v[92:95], v[92:95], v[8:11], 0
	v_mfma_f32_16x16x32_bf16 v[112:115], v[144:147], v[4:7], v[112:115]
	v_mfma_f32_16x16x32_bf16 v[92:95], v[144:147], v[12:15], v[92:95]
	ds_read_b128 v[144:147], v143 offset:4672
	v_mfma_f32_16x16x32_bf16 v[108:111], v[104:107], v[0:3], 0
	v_mfma_f32_16x16x32_bf16 v[104:107], v[104:107], v[8:11], 0
	s_waitcnt lgkmcnt(0)
	v_mfma_f32_16x16x32_bf16 v[108:111], v[144:147], v[4:7], v[108:111]
	v_mfma_f32_16x16x32_bf16 v[104:107], v[144:147], v[12:15], v[104:107]
	v_max3_f32 v143, v120, s49, v121
	v_max3_f32 v143, v143, v122, v123
	v_max3_f32 v143, v143, v116, v117
	v_max3_f32 v143, v143, v118, v119
	v_max3_f32 v143, v143, v112, v113
	v_max3_f32 v143, v143, v114, v115
	s_nop 1
	v_max3_f32 v144, v100, s49, v101
	v_max3_f32 v144, v144, v102, v103
	v_max3_f32 v144, v144, v96, v97
	v_max3_f32 v144, v144, v98, v99
	v_max3_f32 v144, v144, v92, v93
	v_max3_f32 v144, v144, v94, v95
	v_max3_f32 v143, v143, v108, v109
	v_max3_f32 v143, v143, v110, v111
	v_max3_f32 v144, v144, v104, v105
	v_max3_f32 v144, v144, v106, v107
	s_nop 1
	v_permlane32_swap_b32_e32 v143, v144
	v_max_f32_e32 v145, v143, v144
	v_mov_b32_e32 v146, v145
	s_nop 1
	v_permlane16_swap_b32_e32 v145, v146
	v_max_f32_e32 v145, v145, v146
	v_mov_b32_e32 v146, v145
	s_nop 1
	v_permlane32_swap_b32_e32 v145, v146
	v_mov_b32_e32 v142, 0x7f61b1e6
	v_max_f32_e32 v145, v141, v145
	v_cndmask_b32_e32 v143, v141, v145, vcc
	v_cndmask_b32_e32 v142, v142, v143, vcc
	v_cmp_ne_u32_e32 vcc, 0, v140
	v_mov_b32_e32 v140, 0x7f61b1e6
	v_max_f32_e32 v146, v139, v146
	v_cndmask_b32_e32 v144, v139, v146, vcc
	s_nop 0
	v_cndmask_b32_e32 v140, v140, v144, vcc
	v_pk_add_f32 v[120:121], v[120:121], v[142:143] op_sel_hi:[1,0] neg_lo:[0,1] neg_hi:[0,1]
	v_pk_add_f32 v[122:123], v[122:123], v[142:143] op_sel_hi:[1,0] neg_lo:[0,1] neg_hi:[0,1]
	v_pk_add_f32 v[116:117], v[116:117], v[142:143] op_sel_hi:[1,0] neg_lo:[0,1] neg_hi:[0,1]
	v_pk_add_f32 v[118:119], v[118:119], v[142:143] op_sel_hi:[1,0] neg_lo:[0,1] neg_hi:[0,1]
	v_pk_add_f32 v[112:113], v[112:113], v[142:143] op_sel_hi:[1,0] neg_lo:[0,1] neg_hi:[0,1]
	v_pk_add_f32 v[114:115], v[114:115], v[142:143] op_sel_hi:[1,0] neg_lo:[0,1] neg_hi:[0,1]
	v_pk_add_f32 v[108:109], v[108:109], v[142:143] op_sel_hi:[1,0] neg_lo:[0,1] neg_hi:[0,1]
	v_pk_add_f32 v[110:111], v[110:111], v[142:143] op_sel_hi:[1,0] neg_lo:[0,1] neg_hi:[0,1]
	v_sub_f32_e32 v141, v141, v143
	v_sub_f32_e32 v100, v100, v140
	v_exp_f32_e32 v120, v120
	v_exp_f32_e32 v121, v121
	v_exp_f32_e32 v122, v122
	v_exp_f32_e32 v123, v123
	v_exp_f32_e32 v116, v116
	v_exp_f32_e32 v117, v117
	v_exp_f32_e32 v118, v118
	v_exp_f32_e32 v119, v119
	v_exp_f32_e32 v112, v112
	v_exp_f32_e32 v113, v113
	v_exp_f32_e32 v114, v114
	v_exp_f32_e32 v115, v115
	v_exp_f32_e32 v147, v108
	v_exp_f32_e32 v109, v109
	v_exp_f32_e32 v110, v110
	v_exp_f32_e32 v111, v111
	v_add_f32_e32 v145, 0, v120
	v_add_f32_e32 v145, v121, v145
	v_add_f32_e32 v145, v122, v145
	v_add_f32_e32 v145, v123, v145
	v_add_f32_e32 v145, v116, v145
	v_add_f32_e32 v145, v117, v145
	v_add_f32_e32 v145, v118, v145
	v_add_f32_e32 v145, v119, v145
	v_add_f32_e32 v145, v112, v145
	v_add_f32_e32 v145, v113, v145
	v_add_f32_e32 v145, v114, v145
	v_add_f32_e32 v145, v115, v145
	v_add_f32_e32 v108, v147, v145
	v_add_f32_e32 v108, v109, v108
	v_add_f32_e32 v108, v110, v108
	v_add_f32_e32 v145, v111, v108
	v_exp_f32_e32 v108, v141
	v_exp_f32_e32 v100, v100
	v_sub_f32_e32 v101, v101, v140
	v_exp_f32_e32 v101, v101
	v_sub_f32_e32 v102, v102, v140
	v_exp_f32_e32 v102, v102
	v_sub_f32_e32 v103, v103, v140
	v_exp_f32_e32 v103, v103
	v_sub_f32_e32 v96, v96, v140
; template <bool BOUNDARY, bool Q0, bool Q1>
; __device__ __forceinline__ void attn_tile(const bf16* Ks, const bf16* Vt, const bf16x8 (&Qf)[2][2], const uint32_t (&vm)[2],
;                                           float (&m)[2], float (&l)[2], f32x4 (&O)[4][2], int fr, int fq) {
;     ...
;     const float alpha = __builtin_amdgcn_exp2f(m[qt] - mx);
;     m[qt] = mx;
;     float ls = 0.f;
; #pragma unroll
;     for (int kt = 0; kt < 4; ++kt)
; #pragma unroll
;       for (int j = 0; j < 4; ++j) {
;         float pv;
;         if (BOUNDARY) pv = ((vm[qt] >> (kt * 4 + j)) & 1u) ? __builtin_amdgcn_exp2f(S[kt][qt][j] - mxu) : 0.f;
;         else pv = __builtin_amdgcn_exp2f(S[kt][qt][j] - mxu);
;         S[kt][qt][j] = pv;
;         ls += pv;
;       }
;     l[qt] = l[qt] * alpha + ls;
; #pragma unroll
;     for (int dt = 0; dt < 4; ++dt) {
;       O[dt][qt][0] *= alpha; O[dt][qt][1] *= alpha; O[dt][qt][2] *= alpha; O[dt][qt][3] *= alpha;
;     }
;   }
; #pragma unroll
;   for (int kp = 0; kp < 2; ++kp) {
;     bf16x8 Pf[2];
; #pragma unroll
;     for (int qt = 0; qt < 2; ++qt) {
;       const u32x4 pk = {pack2(S[2 * kp][qt][0], S[2 * kp][qt][1]), pack2(S[2 * kp][qt][2], S[2 * kp][qt][3]),
;                         pack2(S[2 * kp + 1][qt][0], S[2 * kp + 1][qt][1]), pack2(S[2 * kp + 1][qt][2], S[2 * kp + 1][qt][3])};
;       Pf[qt] = __builtin_bit_cast(bf16x8, pk);
;     }
; #pragma unroll
;     for (int dt = 0; dt < 4; ++dt) {
;       const bf16x4 v0 = *(const bf16x4*)(Vt + (16 * dt + fr) * VT_LD + 32 * kp + 4 * fq);
;       const bf16x4 v1 = *(const bf16x4*)(Vt + (16 * dt + fr) * VT_LD + 32 * kp + 16 + 4 * fq);
;       bf16x8 vf;
;       vf[0] = v0[0]; vf[1] = v0[1]; vf[2] = v0[2]; vf[3] = v0[3];
;       vf[4] = v1[0]; vf[5] = v1[1]; vf[6] = v1[2]; vf[7] = v1[3];
;       if (Q0) O[dt][0] = __builtin_amdgcn_mfma_f32_16x16x32_bf16(vf, Pf[0], O[dt][0], 0, 0, 0);
;       if (Q1) O[dt][1] = __builtin_amdgcn_mfma_f32_16x16x32_bf16(vf, Pf[1], O[dt][1], 0, 0, 0);
;     }
;   }
	v_fmac_f32_e32 v145, v132, v108
	v_pk_mul_f32 v[90:91], v[90:91], v[108:109] op_sel_hi:[1,0]
	v_pk_mul_f32 v[88:89], v[88:89], v[108:109] op_sel_hi:[1,0]
	v_pk_mul_f32 v[86:87], v[86:87], v[108:109] op_sel_hi:[1,0]
	v_pk_mul_f32 v[84:85], v[84:85], v[108:109] op_sel_hi:[1,0]
	v_pk_mul_f32 v[82:83], v[82:83], v[108:109] op_sel_hi:[1,0]
	v_pk_mul_f32 v[80:81], v[80:81], v[108:109] op_sel_hi:[1,0]
	v_pk_mul_f32 v[78:79], v[78:79], v[108:109] op_sel_hi:[1,0]
	v_pk_mul_f32 v[76:77], v[76:77], v[108:109] op_sel_hi:[1,0]
	v_sub_f32_e32 v108, v139, v144
	v_add_f32_e32 v132, 0, v100
	v_exp_f32_e32 v139, v96
	v_add_f32_e32 v132, v101, v132
	v_add_f32_e32 v132, v102, v132
	v_add_f32_e32 v132, v103, v132
	v_sub_f32_e32 v97, v97, v140
	v_add_f32_e32 v96, v139, v132
	v_exp_f32_e32 v132, v97
	v_sub_f32_e32 v97, v98, v140
	v_exp_f32_e32 v141, v97
	v_sub_f32_e32 v97, v99, v140
	v_exp_f32_e32 v99, v97
	v_sub_f32_e32 v92, v92, v140
	v_exp_f32_e32 v142, v92
	v_sub_f32_e32 v93, v93, v140
	v_add_f32_e32 v96, v132, v96
	v_exp_f32_e32 v148, v93
	v_sub_f32_e32 v93, v94, v140
	v_add_f32_e32 v96, v141, v96
	v_exp_f32_e32 v149, v93
	v_sub_f32_e32 v93, v95, v140
	v_add_f32_e32 v96, v99, v96
	v_exp_f32_e32 v150, v93
	v_sub_f32_e32 v93, v104, v140
	v_add_f32_e32 v92, v142, v96
	v_exp_f32_e32 v104, v93
	v_sub_f32_e32 v93, v105, v140
	v_add_f32_e32 v92, v148, v92
	v_exp_f32_e32 v105, v93
	v_sub_f32_e32 v93, v106, v140
	v_add_f32_e32 v92, v149, v92
	v_exp_f32_e32 v106, v93
	v_sub_f32_e32 v93, v107, v140
	v_add_f32_e32 v92, v150, v92
	v_exp_f32_e32 v107, v93
	v_add_f32_e32 v92, v104, v92
	v_add_f32_e32 v92, v105, v92
	v_add_f32_e32 v92, v106, v92
	v_add_f32_e32 v146, v107, v92
	v_exp_f32_e32 v92, v108
	v_lshlrev_b32_e32 v108, 1, v223
	v_cvt_pk_bf16_f32 v96, v100, v101
	v_add3_u32 v100, v138, v231, v108
	v_fmac_f32_e32 v146, v133, v92
	v_pk_mul_f32 v[74:75], v[74:75], v[92:93] op_sel_hi:[1,0]
	v_pk_mul_f32 v[72:73], v[72:73], v[92:93] op_sel_hi:[1,0]
	v_pk_mul_f32 v[70:71], v[70:71], v[92:93] op_sel_hi:[1,0]
	v_pk_mul_f32 v[68:69], v[68:69], v[92:93] op_sel_hi:[1,0]
	v_pk_mul_f32 v[66:67], v[66:67], v[92:93] op_sel_hi:[1,0]
	v_pk_mul_f32 v[64:65], v[64:65], v[92:93] op_sel_hi:[1,0]
	v_pk_mul_f32 v[62:63], v[62:63], v[92:93] op_sel_hi:[1,0]
	v_pk_mul_f32 v[60:61], v[60:61], v[92:93] op_sel_hi:[1,0]
	v_cvt_pk_bf16_f32 v92, v120, v121
	v_add_u32_e32 v120, 0x2000, v100
	v_cvt_pk_bf16_f32 v97, v102, v103
	v_cvt_pk_bf16_f32 v93, v122, v123
	ds_read2_b64 v[100:103], v120 offset0:128 offset1:132
	v_cvt_pk_bf16_f32 v94, v116, v117
	v_cvt_pk_bf16_f32 v95, v118, v119
	v_cvt_pk_bf16_f32 v98, v139, v132
	v_cvt_pk_bf16_f32 v99, v141, v99
	v_lshlrev_b32_e32 v132, 1, v233
	v_add3_u32 v108, v138, v132, v108
	v_add_u32_e32 v121, 0x2000, v108
	v_add_u32_e32 v122, 0x2800, v108
	v_add_u32_e32 v123, 0x3000, v108
	v_cvt_pk_bf16_f32 v116, v112, v113
	v_cvt_pk_bf16_f32 v117, v114, v115
	ds_read2_b64 v[112:115], v122 offset0:144 offset1:148
	v_cvt_pk_bf16_f32 v118, v147, v109
	v_cvt_pk_bf16_f32 v119, v110, v111
	ds_read2_b64 v[108:111], v123 offset0:160 offset1:164
	v_cvt_pk_bf16_f32 v138, v142, v148
	v_cvt_pk_bf16_f32 v139, v149, v150
	v_cvt_pk_bf16_f32 v140, v104, v105
	v_cvt_pk_bf16_f32 v141, v106, v107
	ds_read2_b64 v[104:107], v121 offset0:128 offset1:132
	s_waitcnt lgkmcnt(3)
	v_mfma_f32_16x16x32_bf16 v[88:91], v[100:103], v[92:95], v[88:91]
	v_mfma_f32_16x16x32_bf16 v[72:75], v[100:103], v[96:99], v[72:75]
	ds_read2_b64 v[100:103], v120 offset0:136 offset1:140
	s_waitcnt lgkmcnt(3)
	v_mfma_f32_16x16x32_bf16 v[80:83], v[112:115], v[92:95], v[80:83]
	v_mfma_f32_16x16x32_bf16 v[64:67], v[112:115], v[96:99], v[64:67]
	ds_read2_b64 v[112:115], v122 offset0:152 offset1:156
	s_waitcnt lgkmcnt(3)
	v_mfma_f32_16x16x32_bf16 v[76:79], v[108:111], v[92:95], v[76:79]
	v_mfma_f32_16x16x32_bf16 v[60:63], v[108:111], v[96:99], v[60:63]
	ds_read2_b64 v[108:111], v121 offset0:136 offset1:140
	s_waitcnt lgkmcnt(3)
	v_mfma_f32_16x16x32_bf16 v[84:87], v[104:107], v[92:95], v[84:87]
	v_mfma_f32_16x16x32_bf16 v[68:71], v[104:107], v[96:99], v[68:71]
	ds_read2_b64 v[148:151], v123 offset0:168 offset1:172
	s_waitcnt lgkmcnt(3)
	v_mfma_f32_16x16x32_bf16 v[92:95], v[100:103], v[138:141], v[72:75]
	v_mfma_f32_16x16x32_bf16 v[100:103], v[100:103], v[116:119], v[88:91]
	s_waitcnt lgkmcnt(2)
	v_mfma_f32_16x16x32_bf16 v[104:107], v[112:115], v[138:141], v[64:67]
	v_mfma_f32_16x16x32_bf16 v[112:115], v[112:115], v[116:119], v[80:83]
	s_waitcnt lgkmcnt(1)
	v_mfma_f32_16x16x32_bf16 v[96:99], v[108:111], v[138:141], v[68:71]
	v_mfma_f32_16x16x32_bf16 v[108:111], v[108:111], v[116:119], v[84:87]
	s_waitcnt lgkmcnt(0)
	v_mfma_f32_16x16x32_bf16 v[120:123], v[148:151], v[116:119], v[76:79]
	v_mfma_f32_16x16x32_bf16 v[116:119], v[148:151], v[138:141], v[60:63]
